# HGRN2 mixer part 2: the four segment-sum LDS reads of the prefix are issued together (three exposed LDS round trips removed)
# speedup vs baseline: 1.0067x; 1.0050x over previous
; #define LAS __attribute__((address_space(3)))
; __device__ __forceinline__ float exp2_(float x) { return __builtin_amdgcn_exp2f(x); }
; template <int DK, bool IS_A, int NDV>
; __device__ __forceinline__ void mix_stream(const Params& p, LAS unsigned char* lds, int l, int rs, int T, int h, int dir, int dvh) {
;     ...
;                 float pre0 = 0.f, pre1 = 0.f, ref0 = 0.f, ref1 = 0.f, tot0 = 0.f, tot1 = 0.f;
; #pragma unroll
;                 for (int s8 = 0; s8 < 8; ++s8) { const f32x2 v = *(const LAS f32x2*)(seg + s8 * DK + 2 * cp);
;                     if (s8 < sg) { pre0 += v.x; pre1 += v.y; } if (s8 < 4) { ref0 += v.x; ref1 += v.y; } tot0 += v.x; tot1 += v.y; }
;                 f32x2 E = (f32x2){exp2_(fminf(fmaxf(pre0 - ref0, -115.f), 115.f)), exp2_(fminf(fmaxf(pre1 - ref1, -115.f), 115.f))};
.LBB0_175:
	ds_read2st64_b64 v[0:3], v108 offset1:1
	ds_read2st64_b64 v[204:207], v108 offset0:2 offset1:3
	ds_read2st64_b64 v[208:211], v108 offset0:4 offset1:5
	ds_read2st64_b64 v[212:215], v108 offset0:6 offset1:7
	v_exp_f32_e32 v104, v104
	v_exp_f32_e32 v105, v105
	v_exp_f32_e32 v102, v102
	v_exp_f32_e32 v103, v103
	s_waitcnt lgkmcnt(3)
	v_add_f32_e32 v0, 0, v0
	v_add_f32_e32 v1, 0, v1
	v_cndmask_b32_e64 v4, 0, v1, s[58:59]
	v_cndmask_b32_e64 v5, 0, v0, s[58:59]
	v_add_f32_e32 v6, v2, v5
	v_add_f32_e32 v7, v3, v4
	v_cndmask_b32_e64 v4, v4, v7, s[60:61]
	v_cndmask_b32_e64 v5, v5, v6, s[60:61]
	v_add_f32_e32 v6, v0, v2
	v_add_f32_e32 v7, v1, v3

; #define LAS __attribute__((address_space(3)))
; __device__ __forceinline__ float exp2_(float x) { return __builtin_amdgcn_exp2f(x); }
; template <int DK, bool IS_A, int NDV>
; __device__ __forceinline__ void mix_stream(const Params& p, LAS unsigned char* lds, int l, int rs, int T, int h, int dir, int dvh) {
;     ...
;                 for (int s8 = 0; s8 < 8; ++s8) { const f32x2 v = *(const LAS f32x2*)(seg + s8 * DK + 2 * cp);
;                     if (s8 < sg) { pre0 += v.x; pre1 += v.y; } if (s8 < 4) { ref0 += v.x; ref1 += v.y; } tot0 += v.x; tot1 += v.y; }
;                 f32x2 E = (f32x2){exp2_(fminf(fmaxf(pre0 - ref0, -115.f), 115.f)), exp2_(fminf(fmaxf(pre1 - ref1, -115.f), 115.f))};
	v_exp_f32_e32 v100, v100
	v_exp_f32_e32 v101, v101
	v_exp_f32_e32 v98, v98
	v_exp_f32_e32 v99, v99
	s_waitcnt lgkmcnt(2)
	v_add_f32_e32 v166, v204, v5
	v_add_f32_e32 v167, v205, v4
	v_cndmask_b32_e64 v4, v4, v167, s[62:63]
	v_cndmask_b32_e64 v5, v5, v166, s[62:63]
	v_add_f32_e32 v0, v6, v204
	v_add_f32_e32 v1, v7, v205
	v_add_f32_e32 v6, v206, v5
	v_add_f32_e32 v7, v207, v4
	v_add_f32_e32 v167, v0, v206
	v_add_f32_e32 v166, v1, v207

; #define LAS __attribute__((address_space(3)))
; __device__ __forceinline__ float exp2_(float x) { return __builtin_amdgcn_exp2f(x); }
; template <int DK, bool IS_A, int NDV>
; __device__ __forceinline__ void mix_stream(const Params& p, LAS unsigned char* lds, int l, int rs, int T, int h, int dir, int dvh) {
;     ...
;                 for (int s8 = 0; s8 < 8; ++s8) { const f32x2 v = *(const LAS f32x2*)(seg + s8 * DK + 2 * cp);
;                     if (s8 < sg) { pre0 += v.x; pre1 += v.y; } if (s8 < 4) { ref0 += v.x; ref1 += v.y; } tot0 += v.x; tot1 += v.y; }
;                 f32x2 E = (f32x2){exp2_(fminf(fmaxf(pre0 - ref0, -115.f), 115.f)), exp2_(fminf(fmaxf(pre1 - ref1, -115.f), 115.f))};
	v_cndmask_b32_e64 v4, v4, v7, s[64:65]
	v_cndmask_b32_e64 v5, v5, v6, s[64:65]
	v_exp_f32_e32 v96, v96
	v_exp_f32_e32 v97, v97
	s_waitcnt lgkmcnt(1)
	v_add_f32_e32 v6, v208, v5
	v_add_f32_e32 v7, v209, v4
	v_cndmask_b32_e64 v4, v4, v7, s[66:67]
	v_cndmask_b32_e64 v5, v5, v6, s[66:67]
	v_add_f32_e32 v6, v210, v5
	v_add_f32_e32 v7, v211, v4
	v_cndmask_b32_e64 v168, v4, v7, s[68:69]
	v_cndmask_b32_e64 v169, v5, v6, s[68:69]

; #define LAS __attribute__((address_space(3)))
; __device__ __forceinline__ unsigned cvt_pk_bf16(float lo, float hi) { unsigned r; asm("v_cvt_pk_bf16_f32 %0, %1, %2" : "=v"(r) : "v"(lo), "v"(hi)); return r; }
; template <int DK, bool IS_A, int NDV>
; __device__ __forceinline__ void mix_stream(const Params& p, LAS unsigned char* lds, int l, int rs, int T, int h, int dir, int dvh) {
;     ...
;                 for (int s8 = 0; s8 < 8; ++s8) { const f32x2 v = *(const LAS f32x2*)(seg + s8 * DK + 2 * cp);
;                     if (s8 < sg) { pre0 += v.x; pre1 += v.y; } if (s8 < 4) { ref0 += v.x; ref1 += v.y; } tot0 += v.x; tot1 += v.y; }
;                 f32x2 E = (f32x2){exp2_(fminf(fmaxf(pre0 - ref0, -115.f), 115.f)), exp2_(fminf(fmaxf(pre1 - ref1, -115.f), 115.f))};
; #pragma unroll
;                 for (int ip = 0; ip < 4; ++ip) { unsigned kp[2];
; #pragma unroll
;                     for (int e = 0; e < 2; ++e) { const int i = 2 * ip + e;
;                         const f32x2 f = (f32x2){exp2_(bf_lo(rf[par][i])), exp2_(bf_hi(rf[par][i]))};
;                         E = __builtin_elementwise_max(E * f, (f32x2){1e-35f, 1e-35f});
;                         const f32x2 r = (f32x2){rcp_(E.x), rcp_(E.y)};
;                         const f32x2 k = r - f * r;
;                         const f32x2 qv = (f32x2){bf_lo(rq[par][i]), bf_hi(rq[par][i])} * E;
;                         const int t = sg * 8 + i;
;                         const int cb4 = (4 * cp) ^ ((i >= 4 ? 16 : 0) ^ sgx);
;                         *(LAS unsigned*)(Qs + t * QP + cb4) = cvt_pk_bf16(qv.x, qv.y);
;                         kp[e] = cvt_pk_bf16(k.x, k.y);
;                         *(LAS unsigned*)(Ks + t * QP + cb4) = kp[e]; }
;                     kt0[ip] = __builtin_amdgcn_perm(kp[1], kp[0], 0x05040100u); kt1[ip] = __builtin_amdgcn_perm(kp[1], kp[0], 0x07060302u);
;                     vt0[ip] = __builtin_amdgcn_perm(rv[par][2 * ip + 1], rv[par][2 * ip], 0x05040100u); vt1[ip] = __builtin_amdgcn_perm(rv[par][2 * ip + 1], rv[par][2 * ip], 0x07060302u);
;                 }
;                 if (sg == 0) { *(LAS f32x2*)(cdec + 2 * cp) = (f32x2){exp2_(fmaxf(tot0, -115.f)), exp2_(fmaxf(tot1, -115.f))};
;                                *(LAS f32x2*)(csc + 2 * cp) = (f32x2){exp2_(fmaxf(tot0 - ref0, -115.f)), exp2_(fmaxf(tot1 - ref1, -115.f))}; }
	v_add_u32_e32 v172, s9, v112
	v_exp_f32_e32 v94, v94
	v_exp_f32_e32 v95, v95
	v_exp_f32_e32 v92, v92
	s_waitcnt lgkmcnt(0)
	v_add_f32_e32 v170, v212, v169
	v_add_f32_e32 v171, v213, v168
	v_cndmask_b32_e64 v168, v168, v171, s[70:71]
	v_cndmask_b32_e64 v169, v169, v170, s[70:71]
	v_add_f32_e32 v170, v214, v169
	v_add_f32_e32 v171, v215, v168
	v_cndmask_b32_e64 v171, v168, v171, s[72:73]
	v_cndmask_b32_e64 v168, v169, v170, s[72:73]
	v_sub_f32_e32 v168, v168, v167
	v_sub_f32_e32 v169, v171, v166
	v_med3_f32 v168, v168, s2, v240
	v_med3_f32 v169, v169, s2, v240
	v_exp_f32_e32 v168, v168
	v_exp_f32_e32 v169, v169
	v_exp_f32_e32 v93, v93
	v_exp_f32_e32 v90, v90
	v_exp_f32_e32 v91, v91
	v_pk_mul_f32 v[168:169], v[104:105], v[168:169]
	s_andn2_b64 vcc, exec, s[0:1]
	v_max_f32_e32 v169, 0x554ad2e, v169
	v_max_f32_e32 v168, 0x554ad2e, v168
	v_rcp_f32_e32 v170, v168
	v_rcp_f32_e32 v171, v169
	s_nop 0
	v_pk_fma_f32 v[104:105], v[104:105], v[170:171], v[170:171] neg_lo:[1,0,0] neg_hi:[1,0,0]
	v_lshlrev_b32_e32 v170, 16, v122
	v_and_b32_e32 v171, 0xffff0000, v122
	v_pk_mul_f32 v[170:171], v[168:169], v[170:171]
	v_pk_mul_f32 v[168:169], v[102:103], v[168:169]
	v_cvt_pk_bf16_f32 v170, v170, v171
	v_add_u32_e32 v171, s8, v112
	v_max_f32_e32 v169, 0x554ad2e, v169
	v_max_f32_e32 v168, 0x554ad2e, v168
	v_cvt_pk_bf16_f32 v104, v104, v105
	ds_write2st64_b32 v171, v170, v104 offset1:68
	v_rcp_f32_e32 v170, v168
	v_rcp_f32_e32 v171, v169
	s_nop 0
	v_pk_fma_f32 v[102:103], v[102:103], v[170:171], v[170:171] neg_lo:[1,0,0] neg_hi:[1,0,0]
	v_lshlrev_b32_e32 v170, 16, v124
	v_and_b32_e32 v171, 0xffff0000, v124
	v_pk_mul_f32 v[170:171], v[168:169], v[170:171]
	v_pk_mul_f32 v[168:169], v[100:101], v[168:169]
	v_cvt_pk_bf16_f32 v105, v170, v171
	v_cvt_pk_bf16_f32 v102, v102, v103
	s_nop 0
	v_max_f32_e32 v169, 0x554ad2e, v169
	v_max_f32_e32 v168, 0x554ad2e, v168
	v_rcp_f32_e32 v170, v168
	v_rcp_f32_e32 v171, v169
	s_nop 0
	v_pk_fma_f32 v[100:101], v[100:101], v[170:171], v[170:171] neg_lo:[1,0,0] neg_hi:[1,0,0]
	v_lshlrev_b32_e32 v170, 16, v129
	v_and_b32_e32 v171, 0xffff0000, v129
	v_pk_mul_f32 v[170:171], v[168:169], v[170:171]
	v_pk_mul_f32 v[168:169], v[98:99], v[168:169]
	v_cvt_pk_bf16_f32 v103, v170, v171
	v_cvt_pk_bf16_f32 v100, v100, v101
	v_add_u32_e32 v101, 0x4400, v172
	v_max_f32_e32 v169, 0x554ad2e, v169
	v_max_f32_e32 v168, 0x554ad2e, v168
	v_rcp_f32_e32 v170, v168
	v_rcp_f32_e32 v171, v169
	ds_write2_b32 v101, v102, v100 offset1:68
	ds_write2_b32 v172, v105, v103 offset1:68
	v_pk_fma_f32 v[98:99], v[98:99], v[170:171], v[170:171] neg_lo:[1,0,0] neg_hi:[1,0,0]
	v_lshlrev_b32_e32 v170, 16, v150
	v_and_b32_e32 v171, 0xffff0000, v150
	v_pk_mul_f32 v[170:171], v[168:169], v[170:171]
	v_pk_mul_f32 v[168:169], v[96:97], v[168:169]
	v_cvt_pk_bf16_f32 v101, v170, v171
	v_cvt_pk_bf16_f32 v98, v98, v99
	ds_write_b32 v172, v101 offset:544
	v_max_f32_e32 v169, 0x554ad2e, v169
	v_max_f32_e32 v168, 0x554ad2e, v168
	v_rcp_f32_e32 v170, v168
	v_rcp_f32_e32 v171, v169
	v_add_u32_e32 v101, 0x200, v133
	ds_write_b32 v172, v98 offset:17952
	v_pk_fma_f32 v[96:97], v[96:97], v[170:171], v[170:171] neg_lo:[1,0,0] neg_hi:[1,0,0]
	v_lshlrev_b32_e32 v170, 16, v153
	v_and_b32_e32 v171, 0xffff0000, v153
	v_pk_mul_f32 v[170:171], v[168:169], v[170:171]
	v_pk_mul_f32 v[168:169], v[94:95], v[168:169]
	v_cvt_pk_bf16_f32 v99, v170, v171
	v_cvt_pk_bf16_f32 v96, v96, v97
	s_nop 0
	v_max_f32_e32 v169, 0x554ad2e, v169
	v_max_f32_e32 v168, 0x554ad2e, v168
	v_rcp_f32_e32 v170, v168
	v_rcp_f32_e32 v171, v169
	s_nop 0
	v_pk_fma_f32 v[94:95], v[94:95], v[170:171], v[170:171] neg_lo:[1,0,0] neg_hi:[1,0,0]
	v_lshlrev_b32_e32 v170, 16, v157
	v_and_b32_e32 v171, 0xffff0000, v157
	v_pk_mul_f32 v[170:171], v[168:169], v[170:171]
	v_pk_mul_f32 v[168:169], v[92:93], v[168:169]
	v_cvt_pk_bf16_f32 v97, v170, v171
	v_cvt_pk_bf16_f32 v94, v94, v95
	v_add_u32_e32 v95, 0x4600, v133
	v_max_f32_e32 v169, 0x554ad2e, v169
	v_max_f32_e32 v168, 0x554ad2e, v168
	v_rcp_f32_e32 v170, v168
	v_rcp_f32_e32 v171, v169
	ds_write2_b32 v95, v96, v94 offset0:76 offset1:144
	ds_write2_b32 v101, v99, v97 offset0:76 offset1:144
	v_add_u32_e32 v97, 0x400, v133
	v_pk_fma_f32 v[92:93], v[92:93], v[170:171], v[170:171] neg_lo:[1,0,0] neg_hi:[1,0,0]
	v_lshlrev_b32_e32 v170, 16, v160
	v_and_b32_e32 v171, 0xffff0000, v160
	v_pk_mul_f32 v[170:171], v[168:169], v[170:171]
	v_pk_mul_f32 v[168:169], v[90:91], v[168:169]
	v_cvt_pk_bf16_f32 v95, v170, v171
	v_cvt_pk_bf16_f32 v92, v92, v93
	s_nop 0
	v_max_f32_e32 v169, 0x554ad2e, v169
	v_max_f32_e32 v168, 0x554ad2e, v168
	v_rcp_f32_e32 v170, v168
	v_rcp_f32_e32 v171, v169
	s_nop 0
	v_pk_fma_f32 v[90:91], v[90:91], v[170:171], v[170:171] neg_lo:[1,0,0] neg_hi:[1,0,0]
	v_lshlrev_b32_e32 v170, 16, v163
	v_and_b32_e32 v171, 0xffff0000, v163
	v_cvt_pk_bf16_f32 v90, v90, v91
	v_add_u32_e32 v91, 0x4800, v133
	v_pk_mul_f32 v[168:169], v[168:169], v[170:171]
	ds_write2_b32 v91, v92, v90 offset0:84 offset1:152
	v_cvt_pk_bf16_f32 v93, v168, v169
	ds_write2_b32 v97, v95, v93 offset0:84 offset1:152
	s_cbranch_vccnz .LBB0_177
	v_add_f32_e32 v1, v166, v209
	v_add_f32_e32 v0, v167, v208
	v_add_f32_e32 v1, v1, v211
	v_add_f32_e32 v0, v0, v210
	v_add_f32_e32 v1, v1, v213
	v_add_f32_e32 v0, v0, v212
	v_add_f32_e32 v3, v1, v215
	v_add_f32_e32 v2, v0, v214
	v_max_f32_e32 v0, 0xc2e60000, v2
	v_max_f32_e32 v1, 0xc2e60000, v3
	v_sub_f32_e32 v2, v2, v167
	v_sub_f32_e32 v3, v3, v166
	v_exp_f32_e32 v0, v0
	v_exp_f32_e32 v1, v1
	v_max_f32_e32 v2, 0xc2e60000, v2
	v_max_f32_e32 v3, 0xc2e60000, v3
	v_exp_f32_e32 v2, v2
	v_exp_f32_e32 v3, v3
	ds_write_b64 v109, v[0:1]
	ds_write_b64 v110, v[2:3]
	v_max_f32_e32 v4, 0xc2e60000, v167
	v_max_f32_e32 v5, 0xc2e60000, v166
	v_exp_f32_e32 v4, v4
	v_exp_f32_e32 v5, v5
	s_nop 0
	ds_write_b64 v109, v[4:5] offset:18432
